# loop-edge edit (7.11): K-loop counter/pointer SALU block moved in front of the loop-back s_barrier in three GEMM loops
# speedup vs baseline: 1.0009x; 1.0009x over previous
; #define PG8_STAGE(bufoff, gbase, voff) do { _Pragma("unroll") for (int _i = 0; _i < 2; ++_i) \
;         __builtin_amdgcn_global_load_lds((const unsigned*)((const char*)(gbase) + (voff)[_i]), (PG8_LAS unsigned*)(lds + (bufoff) + ldsw + _i * 8192), 16, 0, 0); } while (0)
; #define PG8_LDA(dst, b, h) do { _Pragma("unroll") for (int m = 0; m < 4; ++m) _Pragma("unroll") for (int k = 0; k < 2; ++k) dst[m][k] = *(const PG8_LAS bf16x8*)(lds + PG8_SA(b, h) + aoff + m * 2048 + k * 1024); } while (0)
; #define PG8_LDB(dst, b, h) do { _Pragma("unroll") for (int n = 0; n < 2; ++n) _Pragma("unroll") for (int k = 0; k < 2; ++k) dst[n][k] = *(const PG8_LAS bf16x8*)(lds + PG8_SB(b, h) + boff + n * 2048 + k * 1024); } while (0)
; #define PG8_MMA(ai, bj, At, Bt) do { __builtin_amdgcn_s_setprio(1); _Pragma("unroll") for (int m = 0; m < 4; ++m) _Pragma("unroll") for (int n = 0; n < 2; ++n) _Pragma("unroll") for (int k = 0; k < 2; ++k) \
;         acc[ai][bj][m][n] = __builtin_amdgcn_mfma_f32_16x16x32_bf16(Bt[n][k], At[m][k], acc[ai][bj][m][n], 0, 0, 0); __builtin_amdgcn_s_setprio(0); } while (0)
; #define PG8_WAIT_V(n) asm volatile("s_waitcnt vmcnt(" #n ")" ::: "memory")
; #define PG8_WAIT_L(n) asm volatile("s_waitcnt lgkmcnt(" #n ")" ::: "memory")
; #define PG8_BAR __builtin_amdgcn_s_barrier()
; #define PG8_SCHED __builtin_amdgcn_sched_barrier(0)
; template <class Epi, class Sched, bool ALIGN_EPI = false, bool SP2 = false>
; __device__ __forceinline__ void gemm_phase(PG8_LAS unsigned char* lds, const Gemm g, const Sched& S, const Epi& E) {
;     ...
;             PG8_LDB(B0, 0, 0); PG8_LDB(B1, 0, 1); PG8_SCHED; PG8_LDA(At, 0, 0); PG8_STAGE(PG8_SA(1, 1), a1 + hstepA, voffA);
;             PG8_WAIT_V(8); PG8_WAIT_L(0); PG8_BAR; PG8_MMA(0, 0, At, B0); PG8_MMA(0, 1, At, B1); PG8_BAR; PG8_SCHED;
;             PG8_LDA(At, 0, 1); PG8_STAGE(PG8_SB(0, 0), b2, voffB); PG8_STAGE(PG8_SB(0, 1), b2 + hstepB, voffB); PG8_STAGE(PG8_SA(0, 0), a2, voffA);
.LBB0_238:
	ds_read_b128 v[150:153], v147
	ds_read_b128 v[154:157], v147 offset:1024
	ds_read_b128 v[158:161], v147 offset:2048
	ds_read_b128 v[162:165], v147 offset:3072
	ds_read_b128 v[170:173], v148
	ds_read_b128 v[174:177], v148 offset:1024
	ds_read_b128 v[178:181], v148 offset:2048
	ds_read_b128 v[182:185], v148 offset:3072
	s_add_u32 s64, s62, 0xfff80080
	s_addc_u32 s65, s63, -1
	s_cmp_eq_u32 s83, 28
	s_cselect_b32 s67, s45, s65
	s_cselect_b32 s66, s79, s64
	s_cselect_b32 s65, s41, s82
	s_cselect_b32 s64, s80, s81
	v_lshl_add_u64 v[166:167], s[62:63], 0, v[136:137]
	s_add_i32 m0, s43, 0xc000
	ds_read_b128 v[186:189], v149
	ds_read_b128 v[190:193], v149 offset:1024
	ds_read_b128 v[194:197], v149 offset:2048
	ds_read_b128 v[198:201], v149 offset:3072
	ds_read_b128 v[202:205], v149 offset:4096
	ds_read_b128 v[210:213], v149 offset:5120
	ds_read_b128 v[214:217], v149 offset:6144
	ds_read_b128 v[218:221], v149 offset:7168
	global_load_lds_dwordx4 v[166:167], off
	v_lshl_add_u64 v[166:167], s[62:63], 0, v[138:139]
	s_add_i32 m0, s43, 0xe000
	s_nop 0
	global_load_lds_dwordx4 v[166:167], off
	s_waitcnt vmcnt(8)
	s_waitcnt lgkmcnt(0)
	s_barrier
	s_setprio 1
	s_waitcnt lgkmcnt(0)
	v_mfma_f32_16x16x32_bf16 v[124:127], v[150:153], v[186:189], v[124:127]
	v_mfma_f32_16x16x32_bf16 v[120:123], v[158:161], v[186:189], v[120:123]
	v_mfma_f32_16x16x32_bf16 v[116:119], v[150:153], v[194:197], v[116:119]
	v_mfma_f32_16x16x32_bf16 v[112:115], v[158:161], v[194:197], v[112:115]
	v_mfma_f32_16x16x32_bf16 v[100:103], v[150:153], v[202:205], v[100:103]
	v_mfma_f32_16x16x32_bf16 v[96:99], v[158:161], v[202:205], v[96:99]
	v_mfma_f32_16x16x32_bf16 v[84:87], v[150:153], v[214:217], v[84:87]
	v_mfma_f32_16x16x32_bf16 v[80:83], v[158:161], v[214:217], v[80:83]
	v_mfma_f32_16x16x32_bf16 v[124:127], v[154:157], v[190:193], v[124:127]
	v_mfma_f32_16x16x32_bf16 v[120:123], v[162:165], v[190:193], v[120:123]
	v_mfma_f32_16x16x32_bf16 v[116:119], v[154:157], v[198:201], v[116:119]
	v_mfma_f32_16x16x32_bf16 v[112:115], v[162:165], v[198:201], v[112:115]
	v_mfma_f32_16x16x32_bf16 v[100:103], v[154:157], v[210:213], v[100:103]
	v_mfma_f32_16x16x32_bf16 v[96:99], v[162:165], v[210:213], v[96:99]
	v_mfma_f32_16x16x32_bf16 v[84:87], v[154:157], v[218:221], v[84:87]
	v_mfma_f32_16x16x32_bf16 v[80:83], v[162:165], v[218:221], v[80:83]
	s_setprio 0
	s_setprio 1
	v_mfma_f32_16x16x32_bf16 v[108:111], v[170:173], v[186:189], v[108:111]
	v_mfma_f32_16x16x32_bf16 v[104:107], v[178:181], v[186:189], v[104:107]
	v_mfma_f32_16x16x32_bf16 v[92:95], v[170:173], v[194:197], v[92:95]
	v_mfma_f32_16x16x32_bf16 v[88:91], v[178:181], v[194:197], v[88:91]
	v_mfma_f32_16x16x32_bf16 v[76:79], v[170:173], v[202:205], v[76:79]
	v_mfma_f32_16x16x32_bf16 v[72:75], v[178:181], v[202:205], v[72:75]
	v_mfma_f32_16x16x32_bf16 v[68:71], v[170:173], v[214:217], v[68:71]
	v_mfma_f32_16x16x32_bf16 v[64:67], v[178:181], v[214:217], v[64:67]
	v_mfma_f32_16x16x32_bf16 v[108:111], v[174:177], v[190:193], v[108:111]
	v_mfma_f32_16x16x32_bf16 v[104:107], v[182:185], v[190:193], v[104:107]
	v_mfma_f32_16x16x32_bf16 v[92:95], v[174:177], v[198:201], v[92:95]
	v_mfma_f32_16x16x32_bf16 v[88:91], v[182:185], v[198:201], v[88:91]
	v_mfma_f32_16x16x32_bf16 v[76:79], v[174:177], v[210:213], v[76:79]
	v_mfma_f32_16x16x32_bf16 v[72:75], v[182:185], v[210:213], v[72:75]
	v_mfma_f32_16x16x32_bf16 v[68:71], v[174:177], v[218:221], v[68:71]
	v_mfma_f32_16x16x32_bf16 v[64:67], v[182:185], v[218:221], v[64:67]
	s_setprio 0
	s_barrier
	s_add_i32 s84, s77, s33
	v_lshl_add_u64 v[166:167], s[64:65], 0, v[130:131]
	s_mov_b32 m0, s84
	ds_read_b128 v[186:189], v149 offset:16384
	ds_read_b128 v[190:193], v149 offset:17408
	ds_read_b128 v[194:197], v149 offset:18432
	ds_read_b128 v[198:201], v149 offset:19456
	ds_read_b128 v[202:205], v149 offset:20480
	ds_read_b128 v[210:213], v149 offset:21504
	ds_read_b128 v[214:217], v149 offset:22528
	ds_read_b128 v[218:221], v149 offset:23552
	global_load_lds_dwordx4 v[166:167], off
	s_add_i32 m0, s84, 0x2000
	s_add_u32 s84, s64, 0x80000
	v_lshl_add_u64 v[206:207], s[64:65], 0, v[134:135]
	s_addc_u32 s85, s65, 0
	s_add_i32 s93, s78, s33
	global_load_lds_dwordx4 v[206:207], off
	v_lshl_add_u64 v[222:223], s[84:85], 0, v[130:131]
	s_mov_b32 m0, s93
	v_lshl_add_u64 v[224:225], s[66:67], 0, v[132:133]
	global_load_lds_dwordx4 v[222:223], off
	v_lshl_add_u64 v[222:223], s[84:85], 0, v[134:135]
	s_add_i32 m0, s93, 0x2000
	s_nop 0
	global_load_lds_dwordx4 v[222:223], off
	v_lshl_add_u64 v[222:223], s[66:67], 0, v[128:129]
	s_mov_b32 m0, s43
	s_nop 0
	global_load_lds_dwordx4 v[222:223], off
	s_mov_b32 m0, s68
	s_nop 0
	global_load_lds_dwordx4 v[224:225], off
	s_waitcnt vmcnt(8)
	s_waitcnt lgkmcnt(0)
	s_barrier
; #define PG8_STAGE(bufoff, gbase, voff) do { _Pragma("unroll") for (int _i = 0; _i < 2; ++_i) \
;         __builtin_amdgcn_global_load_lds((const unsigned*)((const char*)(gbase) + (voff)[_i]), (PG8_LAS unsigned*)(lds + (bufoff) + ldsw + _i * 8192), 16, 0, 0); } while (0)
; #define PG8_LDA(dst, b, h) do { _Pragma("unroll") for (int m = 0; m < 4; ++m) _Pragma("unroll") for (int k = 0; k < 2; ++k) dst[m][k] = *(const PG8_LAS bf16x8*)(lds + PG8_SA(b, h) + aoff + m * 2048 + k * 1024); } while (0)
; #define PG8_LDB(dst, b, h) do { _Pragma("unroll") for (int n = 0; n < 2; ++n) _Pragma("unroll") for (int k = 0; k < 2; ++k) dst[n][k] = *(const PG8_LAS bf16x8*)(lds + PG8_SB(b, h) + boff + n * 2048 + k * 1024); } while (0)
; #define PG8_MMA(ai, bj, At, Bt) do { __builtin_amdgcn_s_setprio(1); _Pragma("unroll") for (int m = 0; m < 4; ++m) _Pragma("unroll") for (int n = 0; n < 2; ++n) _Pragma("unroll") for (int k = 0; k < 2; ++k) \
;         acc[ai][bj][m][n] = __builtin_amdgcn_mfma_f32_16x16x32_bf16(Bt[n][k], At[m][k], acc[ai][bj][m][n], 0, 0, 0); __builtin_amdgcn_s_setprio(0); } while (0)
; #define PG8_WAIT_V(n) asm volatile("s_waitcnt vmcnt(" #n ")" ::: "memory")
; #define PG8_WAIT_L(n) asm volatile("s_waitcnt lgkmcnt(" #n ")" ::: "memory")
; #define PG8_BAR __builtin_amdgcn_s_barrier()
; #define PG8_SCHED __builtin_amdgcn_sched_barrier(0)
; template <class Epi, class Sched, bool ALIGN_EPI = false, bool SP2 = false>
; __device__ __forceinline__ void gemm_phase(PG8_LAS unsigned char* lds, const Gemm g, const Sched& S, const Epi& E) {
;     ...
;             PG8_WAIT_V(8); PG8_WAIT_L(0); PG8_BAR; PG8_MMA(1, 0, At, B0); PG8_MMA(1, 1, At, B1); PG8_BAR; PG8_SCHED;
;             PG8_LDB(B0, 1, 0); PG8_LDB(B1, 1, 1); PG8_SCHED; PG8_LDA(At, 1, 0); PG8_STAGE(PG8_SA(0, 1), a2 + hstepA, voffA);
;             PG8_WAIT_V(8); PG8_WAIT_L(0); PG8_BAR; PG8_MMA(0, 0, At, B0); PG8_MMA(0, 1, At, B1); PG8_BAR; PG8_SCHED;
	s_setprio 1
	s_waitcnt lgkmcnt(0)
	v_mfma_f32_16x16x32_bf16 v[60:63], v[150:153], v[186:189], v[60:63]
	v_mfma_f32_16x16x32_bf16 v[56:59], v[158:161], v[186:189], v[56:59]
	v_mfma_f32_16x16x32_bf16 v[52:55], v[150:153], v[194:197], v[52:55]
	v_mfma_f32_16x16x32_bf16 v[48:51], v[158:161], v[194:197], v[48:51]
	v_mfma_f32_16x16x32_bf16 v[36:39], v[150:153], v[202:205], v[36:39]
	v_mfma_f32_16x16x32_bf16 v[32:35], v[158:161], v[202:205], v[32:35]
	v_mfma_f32_16x16x32_bf16 v[20:23], v[150:153], v[214:217], v[20:23]
	v_mfma_f32_16x16x32_bf16 v[16:19], v[158:161], v[214:217], v[16:19]
	v_mfma_f32_16x16x32_bf16 v[60:63], v[154:157], v[190:193], v[60:63]
	v_mfma_f32_16x16x32_bf16 v[56:59], v[162:165], v[190:193], v[56:59]
	v_mfma_f32_16x16x32_bf16 v[52:55], v[154:157], v[198:201], v[52:55]
	v_mfma_f32_16x16x32_bf16 v[48:51], v[162:165], v[198:201], v[48:51]
	v_mfma_f32_16x16x32_bf16 v[36:39], v[154:157], v[210:213], v[36:39]
	v_mfma_f32_16x16x32_bf16 v[32:35], v[162:165], v[210:213], v[32:35]
	v_mfma_f32_16x16x32_bf16 v[20:23], v[154:157], v[218:221], v[20:23]
	v_mfma_f32_16x16x32_bf16 v[16:19], v[162:165], v[218:221], v[16:19]
	s_setprio 0
	s_setprio 1
	v_mfma_f32_16x16x32_bf16 v[44:47], v[170:173], v[186:189], v[44:47]
	v_mfma_f32_16x16x32_bf16 v[40:43], v[178:181], v[186:189], v[40:43]
	v_mfma_f32_16x16x32_bf16 v[28:31], v[170:173], v[194:197], v[28:31]
	v_mfma_f32_16x16x32_bf16 v[24:27], v[178:181], v[194:197], v[24:27]
	v_mfma_f32_16x16x32_bf16 v[12:15], v[170:173], v[202:205], v[12:15]
	v_mfma_f32_16x16x32_bf16 v[8:11], v[178:181], v[202:205], v[8:11]
	v_mfma_f32_16x16x32_bf16 v[4:7], v[170:173], v[214:217], v[4:7]
	v_mfma_f32_16x16x32_bf16 v[0:3], v[178:181], v[214:217], v[0:3]
	v_mfma_f32_16x16x32_bf16 v[44:47], v[174:177], v[190:193], v[44:47]
	v_mfma_f32_16x16x32_bf16 v[40:43], v[182:185], v[190:193], v[40:43]
	v_mfma_f32_16x16x32_bf16 v[28:31], v[174:177], v[198:201], v[28:31]
	v_mfma_f32_16x16x32_bf16 v[24:27], v[182:185], v[198:201], v[24:27]
	v_mfma_f32_16x16x32_bf16 v[12:15], v[174:177], v[210:213], v[12:15]
	v_mfma_f32_16x16x32_bf16 v[8:11], v[182:185], v[210:213], v[8:11]
	v_mfma_f32_16x16x32_bf16 v[4:7], v[174:177], v[218:221], v[4:7]
	v_mfma_f32_16x16x32_bf16 v[0:3], v[182:185], v[218:221], v[0:3]
	s_setprio 0
	s_barrier
	s_add_i32 s84, 0, 0x18000
	s_add_i32 s85, 0, 0x1c000
	v_add_u32_e32 v162, s84, v145
	v_add_u32_e32 v169, s85, v145
	ds_read_b128 v[150:153], v162
	ds_read_b128 v[154:157], v162 offset:1024
	ds_read_b128 v[158:161], v162 offset:2048
	ds_read_b128 v[162:165], v162 offset:3072
	ds_read_b128 v[170:173], v169
	ds_read_b128 v[174:177], v169 offset:1024
	ds_read_b128 v[178:181], v169 offset:2048
	ds_read_b128 v[182:185], v169 offset:3072
	s_add_u32 s66, s66, 0x80000
	s_addc_u32 s67, s67, 0
	s_mov_b32 m0, s69
	v_lshl_add_u64 v[226:227], s[66:67], 0, v[128:129]
	ds_read_b128 v[186:189], v149 offset:32768
	ds_read_b128 v[190:193], v149 offset:33792
	ds_read_b128 v[194:197], v149 offset:34816
	ds_read_b128 v[198:201], v149 offset:35840
	ds_read_b128 v[202:205], v149 offset:36864
	ds_read_b128 v[210:213], v149 offset:37888
	ds_read_b128 v[214:217], v149 offset:38912
	ds_read_b128 v[218:221], v149 offset:39936
	global_load_lds_dwordx4 v[226:227], off
	v_lshl_add_u64 v[226:227], s[66:67], 0, v[132:133]
	s_mov_b32 m0, s70
	s_nop 0
	global_load_lds_dwordx4 v[226:227], off
	s_waitcnt vmcnt(8)
	s_waitcnt lgkmcnt(0)
	s_barrier
	s_setprio 1
	s_waitcnt lgkmcnt(0)
	v_mfma_f32_16x16x32_bf16 v[124:127], v[150:153], v[186:189], v[124:127]
	v_mfma_f32_16x16x32_bf16 v[120:123], v[158:161], v[186:189], v[120:123]
	v_mfma_f32_16x16x32_bf16 v[116:119], v[150:153], v[194:197], v[116:119]
	v_mfma_f32_16x16x32_bf16 v[112:115], v[158:161], v[194:197], v[112:115]
	v_mfma_f32_16x16x32_bf16 v[100:103], v[150:153], v[202:205], v[100:103]
	v_mfma_f32_16x16x32_bf16 v[96:99], v[158:161], v[202:205], v[96:99]
	v_mfma_f32_16x16x32_bf16 v[84:87], v[150:153], v[214:217], v[84:87]
	v_mfma_f32_16x16x32_bf16 v[80:83], v[158:161], v[214:217], v[80:83]
	v_mfma_f32_16x16x32_bf16 v[124:127], v[154:157], v[190:193], v[124:127]
	v_mfma_f32_16x16x32_bf16 v[120:123], v[162:165], v[190:193], v[120:123]
	v_mfma_f32_16x16x32_bf16 v[116:119], v[154:157], v[198:201], v[116:119]
	v_mfma_f32_16x16x32_bf16 v[112:115], v[162:165], v[198:201], v[112:115]
	v_mfma_f32_16x16x32_bf16 v[100:103], v[154:157], v[210:213], v[100:103]
	v_mfma_f32_16x16x32_bf16 v[96:99], v[162:165], v[210:213], v[96:99]
	v_mfma_f32_16x16x32_bf16 v[84:87], v[154:157], v[218:221], v[84:87]
	v_mfma_f32_16x16x32_bf16 v[80:83], v[162:165], v[218:221], v[80:83]
	s_setprio 0
	s_setprio 1
	v_mfma_f32_16x16x32_bf16 v[108:111], v[170:173], v[186:189], v[108:111]
	v_mfma_f32_16x16x32_bf16 v[104:107], v[178:181], v[186:189], v[104:107]
	v_mfma_f32_16x16x32_bf16 v[92:95], v[170:173], v[194:197], v[92:95]
	v_mfma_f32_16x16x32_bf16 v[88:91], v[178:181], v[194:197], v[88:91]
	v_mfma_f32_16x16x32_bf16 v[76:79], v[170:173], v[202:205], v[76:79]
	v_mfma_f32_16x16x32_bf16 v[72:75], v[178:181], v[202:205], v[72:75]
	v_mfma_f32_16x16x32_bf16 v[68:71], v[170:173], v[214:217], v[68:71]
	v_mfma_f32_16x16x32_bf16 v[64:67], v[178:181], v[214:217], v[64:67]
	v_mfma_f32_16x16x32_bf16 v[108:111], v[174:177], v[190:193], v[108:111]
	v_mfma_f32_16x16x32_bf16 v[104:107], v[182:185], v[190:193], v[104:107]
	v_mfma_f32_16x16x32_bf16 v[92:95], v[174:177], v[198:201], v[92:95]
	v_mfma_f32_16x16x32_bf16 v[88:91], v[182:185], v[198:201], v[88:91]
	v_mfma_f32_16x16x32_bf16 v[76:79], v[174:177], v[210:213], v[76:79]
	v_mfma_f32_16x16x32_bf16 v[72:75], v[182:185], v[210:213], v[72:75]
	v_mfma_f32_16x16x32_bf16 v[68:71], v[174:177], v[218:221], v[68:71]
	v_mfma_f32_16x16x32_bf16 v[64:67], v[182:185], v[218:221], v[64:67]
	s_setprio 0
	s_barrier
; #define PG8_STAGE(bufoff, gbase, voff) do { _Pragma("unroll") for (int _i = 0; _i < 2; ++_i) \
;         __builtin_amdgcn_global_load_lds((const unsigned*)((const char*)(gbase) + (voff)[_i]), (PG8_LAS unsigned*)(lds + (bufoff) + ldsw + _i * 8192), 16, 0, 0); } while (0)
; #define PG8_LDA(dst, b, h) do { _Pragma("unroll") for (int m = 0; m < 4; ++m) _Pragma("unroll") for (int k = 0; k < 2; ++k) dst[m][k] = *(const PG8_LAS bf16x8*)(lds + PG8_SA(b, h) + aoff + m * 2048 + k * 1024); } while (0)
; #define PG8_MMA(ai, bj, At, Bt) do { __builtin_amdgcn_s_setprio(1); _Pragma("unroll") for (int m = 0; m < 4; ++m) _Pragma("unroll") for (int n = 0; n < 2; ++n) _Pragma("unroll") for (int k = 0; k < 2; ++k) \
;         acc[ai][bj][m][n] = __builtin_amdgcn_mfma_f32_16x16x32_bf16(Bt[n][k], At[m][k], acc[ai][bj][m][n], 0, 0, 0); __builtin_amdgcn_s_setprio(0); } while (0)
; #define PG8_WAIT_V(n) asm volatile("s_waitcnt vmcnt(" #n ")" ::: "memory")
; #define PG8_WAIT_L(n) asm volatile("s_waitcnt lgkmcnt(" #n ")" ::: "memory")
; #define PG8_BAR __builtin_amdgcn_s_barrier()
; #define PG8_SCHED __builtin_amdgcn_sched_barrier(0)
; template <class Epi, class Sched, bool ALIGN_EPI = false, bool SP2 = false>
; __device__ __forceinline__ void gemm_phase(PG8_LAS unsigned char* lds, const Gemm g, const Sched& S, const Epi& E) {
;     ...
;         for (int t = 0; t < nt; t += 2) {
;     ...
;             PG8_LDA(At, 1, 1); PG8_STAGE(PG8_SB(1, 0), b3, voffB); PG8_STAGE(PG8_SB(1, 1), b3 + hstepB, voffB); PG8_STAGE(PG8_SA(1, 0), a3, voffA);
;             PG8_WAIT_V(8); PG8_WAIT_L(0); PG8_BAR; PG8_MMA(1, 0, At, B0); PG8_MMA(1, 1, At, B1); PG8_BAR; PG8_SCHED;
	s_add_i32 s66, s84, s33
	v_lshl_add_u64 v[166:167], v[166:167], 0, s[22:23]
	s_mov_b32 m0, s66
	ds_read_b128 v[186:189], v149 offset:49152
	ds_read_b128 v[190:193], v149 offset:50176
	ds_read_b128 v[194:197], v149 offset:51200
	ds_read_b128 v[198:201], v149 offset:52224
	ds_read_b128 v[202:205], v149 offset:53248
	ds_read_b128 v[210:213], v149 offset:54272
	ds_read_b128 v[214:217], v149 offset:55296
	ds_read_b128 v[218:221], v149 offset:56320
	global_load_lds_dwordx4 v[166:167], off
	s_add_i32 m0, s66, 0x2000
	s_add_u32 s64, s64, 0x80080
	v_lshl_add_u64 v[166:167], v[206:207], 0, s[22:23]
	s_addc_u32 s65, s65, 0
	s_add_i32 s66, s85, s33
	global_load_lds_dwordx4 v[166:167], off
	v_lshl_add_u64 v[166:167], s[64:65], 0, v[130:131]
	s_mov_b32 m0, s66
	s_nop 0
	global_load_lds_dwordx4 v[166:167], off
	v_lshl_add_u64 v[166:167], s[64:65], 0, v[134:135]
	s_add_i32 m0, s66, 0x2000
	s_nop 0
	global_load_lds_dwordx4 v[166:167], off
	v_lshl_add_u64 v[166:167], v[222:223], 0, s[22:23]
	s_mov_b32 m0, s74
	s_nop 0
	global_load_lds_dwordx4 v[166:167], off
	v_lshl_add_u64 v[166:167], v[224:225], 0, s[22:23]
	s_mov_b32 m0, s75
	s_nop 0
	global_load_lds_dwordx4 v[166:167], off
	s_waitcnt vmcnt(8)
	s_waitcnt lgkmcnt(0)
	s_barrier
	s_setprio 1
	s_waitcnt lgkmcnt(0)
	v_mfma_f32_16x16x32_bf16 v[60:63], v[150:153], v[186:189], v[60:63]
	v_mfma_f32_16x16x32_bf16 v[56:59], v[158:161], v[186:189], v[56:59]
	v_mfma_f32_16x16x32_bf16 v[52:55], v[150:153], v[194:197], v[52:55]
	v_mfma_f32_16x16x32_bf16 v[48:51], v[158:161], v[194:197], v[48:51]
	v_mfma_f32_16x16x32_bf16 v[36:39], v[150:153], v[202:205], v[36:39]
	v_mfma_f32_16x16x32_bf16 v[32:35], v[158:161], v[202:205], v[32:35]
	v_mfma_f32_16x16x32_bf16 v[20:23], v[150:153], v[214:217], v[20:23]
	v_mfma_f32_16x16x32_bf16 v[16:19], v[158:161], v[214:217], v[16:19]
	v_mfma_f32_16x16x32_bf16 v[60:63], v[154:157], v[190:193], v[60:63]
	v_mfma_f32_16x16x32_bf16 v[56:59], v[162:165], v[190:193], v[56:59]
	v_mfma_f32_16x16x32_bf16 v[52:55], v[154:157], v[198:201], v[52:55]
	v_mfma_f32_16x16x32_bf16 v[48:51], v[162:165], v[198:201], v[48:51]
	v_mfma_f32_16x16x32_bf16 v[36:39], v[154:157], v[210:213], v[36:39]
	v_mfma_f32_16x16x32_bf16 v[32:35], v[162:165], v[210:213], v[32:35]
	v_mfma_f32_16x16x32_bf16 v[20:23], v[154:157], v[218:221], v[20:23]
	v_mfma_f32_16x16x32_bf16 v[16:19], v[162:165], v[218:221], v[16:19]
	s_setprio 0
	s_setprio 1
	v_mfma_f32_16x16x32_bf16 v[44:47], v[170:173], v[186:189], v[44:47]
	v_mfma_f32_16x16x32_bf16 v[40:43], v[178:181], v[186:189], v[40:43]
	v_mfma_f32_16x16x32_bf16 v[28:31], v[170:173], v[194:197], v[28:31]
	v_mfma_f32_16x16x32_bf16 v[24:27], v[178:181], v[194:197], v[24:27]
	v_mfma_f32_16x16x32_bf16 v[12:15], v[170:173], v[202:205], v[12:15]
	v_mfma_f32_16x16x32_bf16 v[8:11], v[178:181], v[202:205], v[8:11]
	v_mfma_f32_16x16x32_bf16 v[4:7], v[170:173], v[214:217], v[4:7]
	v_mfma_f32_16x16x32_bf16 v[0:3], v[178:181], v[214:217], v[0:3]
	v_mfma_f32_16x16x32_bf16 v[44:47], v[174:177], v[190:193], v[44:47]
	v_mfma_f32_16x16x32_bf16 v[40:43], v[182:185], v[190:193], v[40:43]
	v_mfma_f32_16x16x32_bf16 v[28:31], v[174:177], v[198:201], v[28:31]
	v_mfma_f32_16x16x32_bf16 v[24:27], v[182:185], v[198:201], v[24:27]
	v_mfma_f32_16x16x32_bf16 v[12:15], v[174:177], v[210:213], v[12:15]
	v_mfma_f32_16x16x32_bf16 v[8:11], v[182:185], v[210:213], v[8:11]
	v_mfma_f32_16x16x32_bf16 v[4:7], v[174:177], v[218:221], v[4:7]
	v_mfma_f32_16x16x32_bf16 v[0:3], v[182:185], v[218:221], v[0:3]
	s_setprio 0
	s_add_i32 s83, s83, 2
	s_add_u32 s62, s62, 0x100
	s_addc_u32 s63, s63, 0
	s_add_u32 s81, s81, 0x100
	s_addc_u32 s82, s82, 0
	s_cmp_gt_u32 s83, 29
	s_barrier
	s_cbranch_scc0 .LBB0_238
	s_and_b64 vcc, exec, s[26:27]
	s_cbranch_vccz .LBB0_241
	s_barrier

; #define PG8_STAGE(bufoff, gbase, voff) do { _Pragma("unroll") for (int _i = 0; _i < 2; ++_i) \
;         __builtin_amdgcn_global_load_lds((const unsigned*)((const char*)(gbase) + (voff)[_i]), (PG8_LAS unsigned*)(lds + (bufoff) + ldsw + _i * 8192), 16, 0, 0); } while (0)
; #define PG8_LDA(dst, b, h) do { _Pragma("unroll") for (int m = 0; m < 4; ++m) _Pragma("unroll") for (int k = 0; k < 2; ++k) dst[m][k] = *(const PG8_LAS bf16x8*)(lds + PG8_SA(b, h) + aoff + m * 2048 + k * 1024); } while (0)
; #define PG8_LDB(dst, b, h) do { _Pragma("unroll") for (int n = 0; n < 2; ++n) _Pragma("unroll") for (int k = 0; k < 2; ++k) dst[n][k] = *(const PG8_LAS bf16x8*)(lds + PG8_SB(b, h) + boff + n * 2048 + k * 1024); } while (0)
; #define PG8_MMA(ai, bj, At, Bt) do { __builtin_amdgcn_s_setprio(1); _Pragma("unroll") for (int m = 0; m < 4; ++m) _Pragma("unroll") for (int n = 0; n < 2; ++n) _Pragma("unroll") for (int k = 0; k < 2; ++k) \
;         acc[ai][bj][m][n] = __builtin_amdgcn_mfma_f32_16x16x32_bf16(Bt[n][k], At[m][k], acc[ai][bj][m][n], 0, 0, 0); __builtin_amdgcn_s_setprio(0); } while (0)
; #define PG8_WAIT_V(n) asm volatile("s_waitcnt vmcnt(" #n ")" ::: "memory")
; #define PG8_WAIT_L(n) asm volatile("s_waitcnt lgkmcnt(" #n ")" ::: "memory")
; #define PG8_BAR __builtin_amdgcn_s_barrier()
; #define PG8_SCHED __builtin_amdgcn_sched_barrier(0)
; template <class Epi, class Sched, bool ALIGN_EPI = false, bool SP2 = false>
; __device__ __forceinline__ void gemm_phase(PG8_LAS unsigned char* lds, const Gemm g, const Sched& S, const Epi& E) {
;     ...
;             PG8_LDB(B0, 0, 0); PG8_LDB(B1, 0, 1); PG8_SCHED; PG8_LDA(At, 0, 0); PG8_STAGE(PG8_SA(1, 1), a1 + hstepA, voffA);
;             PG8_WAIT_V(8); PG8_WAIT_L(0); PG8_BAR; PG8_MMA(0, 0, At, B0); PG8_MMA(0, 1, At, B1); PG8_BAR; PG8_SCHED;
;             PG8_LDA(At, 0, 1); PG8_STAGE(PG8_SB(0, 0), b2, voffB); PG8_STAGE(PG8_SB(0, 1), b2 + hstepB, voffB); PG8_STAGE(PG8_SA(0, 0), a2, voffA);
.LBB0_732:
	ds_read_b128 v[150:153], v147
	ds_read_b128 v[154:157], v147 offset:1024
	ds_read_b128 v[158:161], v147 offset:2048
	ds_read_b128 v[162:165], v147 offset:3072
	ds_read_b128 v[170:173], v148
	ds_read_b128 v[174:177], v148 offset:1024
	ds_read_b128 v[178:181], v148 offset:2048
	ds_read_b128 v[182:185], v148 offset:3072
	s_add_u32 s52, s50, 0xfff80080
	s_addc_u32 s53, s51, -1
	s_cmp_eq_u32 s77, 28
	s_cselect_b32 s55, s37, s53
	s_cselect_b32 s54, s71, s52
	s_cselect_b32 s53, s35, s76
	s_cselect_b32 s52, s74, s75
	v_lshl_add_u64 v[166:167], s[50:51], 0, v[136:137]
	s_add_i32 m0, s43, 0xc000
	ds_read_b128 v[186:189], v149
	ds_read_b128 v[190:193], v149 offset:1024
	ds_read_b128 v[194:197], v149 offset:2048
	ds_read_b128 v[198:201], v149 offset:3072
	ds_read_b128 v[202:205], v149 offset:4096
	ds_read_b128 v[210:213], v149 offset:5120
	ds_read_b128 v[214:217], v149 offset:6144
	ds_read_b128 v[218:221], v149 offset:7168
	global_load_lds_dwordx4 v[166:167], off
	v_lshl_add_u64 v[166:167], s[50:51], 0, v[138:139]
	s_add_i32 m0, s43, 0xe000
	s_nop 0
	global_load_lds_dwordx4 v[166:167], off
	s_waitcnt vmcnt(8)
	s_waitcnt lgkmcnt(0)
	s_barrier
	s_setprio 1
	s_waitcnt lgkmcnt(0)
	v_mfma_f32_16x16x32_bf16 v[124:127], v[150:153], v[186:189], v[124:127]
	v_mfma_f32_16x16x32_bf16 v[120:123], v[158:161], v[186:189], v[120:123]
	v_mfma_f32_16x16x32_bf16 v[116:119], v[150:153], v[194:197], v[116:119]
	v_mfma_f32_16x16x32_bf16 v[112:115], v[158:161], v[194:197], v[112:115]
	v_mfma_f32_16x16x32_bf16 v[100:103], v[150:153], v[202:205], v[100:103]
	v_mfma_f32_16x16x32_bf16 v[96:99], v[158:161], v[202:205], v[96:99]
	v_mfma_f32_16x16x32_bf16 v[84:87], v[150:153], v[214:217], v[84:87]
	v_mfma_f32_16x16x32_bf16 v[80:83], v[158:161], v[214:217], v[80:83]
	v_mfma_f32_16x16x32_bf16 v[124:127], v[154:157], v[190:193], v[124:127]
	v_mfma_f32_16x16x32_bf16 v[120:123], v[162:165], v[190:193], v[120:123]
	v_mfma_f32_16x16x32_bf16 v[116:119], v[154:157], v[198:201], v[116:119]
	v_mfma_f32_16x16x32_bf16 v[112:115], v[162:165], v[198:201], v[112:115]
	v_mfma_f32_16x16x32_bf16 v[100:103], v[154:157], v[210:213], v[100:103]
	v_mfma_f32_16x16x32_bf16 v[96:99], v[162:165], v[210:213], v[96:99]
	v_mfma_f32_16x16x32_bf16 v[84:87], v[154:157], v[218:221], v[84:87]
	v_mfma_f32_16x16x32_bf16 v[80:83], v[162:165], v[218:221], v[80:83]
	s_setprio 0
	s_setprio 1
	v_mfma_f32_16x16x32_bf16 v[108:111], v[170:173], v[186:189], v[108:111]
	v_mfma_f32_16x16x32_bf16 v[104:107], v[178:181], v[186:189], v[104:107]
	v_mfma_f32_16x16x32_bf16 v[92:95], v[170:173], v[194:197], v[92:95]
	v_mfma_f32_16x16x32_bf16 v[88:91], v[178:181], v[194:197], v[88:91]
	v_mfma_f32_16x16x32_bf16 v[76:79], v[170:173], v[202:205], v[76:79]
	v_mfma_f32_16x16x32_bf16 v[72:75], v[178:181], v[202:205], v[72:75]
	v_mfma_f32_16x16x32_bf16 v[68:71], v[170:173], v[214:217], v[68:71]
	v_mfma_f32_16x16x32_bf16 v[64:67], v[178:181], v[214:217], v[64:67]
	v_mfma_f32_16x16x32_bf16 v[108:111], v[174:177], v[190:193], v[108:111]
	v_mfma_f32_16x16x32_bf16 v[104:107], v[182:185], v[190:193], v[104:107]
	v_mfma_f32_16x16x32_bf16 v[92:95], v[174:177], v[198:201], v[92:95]
	v_mfma_f32_16x16x32_bf16 v[88:91], v[182:185], v[198:201], v[88:91]
	v_mfma_f32_16x16x32_bf16 v[76:79], v[174:177], v[210:213], v[76:79]
	v_mfma_f32_16x16x32_bf16 v[72:75], v[182:185], v[210:213], v[72:75]
	v_mfma_f32_16x16x32_bf16 v[68:71], v[174:177], v[218:221], v[68:71]
	v_mfma_f32_16x16x32_bf16 v[64:67], v[182:185], v[218:221], v[64:67]
	s_setprio 0
	s_barrier
	s_add_i32 s78, s69, s33
	v_lshl_add_u64 v[166:167], s[52:53], 0, v[130:131]
	s_mov_b32 m0, s78
	ds_read_b128 v[186:189], v149 offset:16384
	ds_read_b128 v[190:193], v149 offset:17408
	ds_read_b128 v[194:197], v149 offset:18432
	ds_read_b128 v[198:201], v149 offset:19456
	ds_read_b128 v[202:205], v149 offset:20480
	ds_read_b128 v[210:213], v149 offset:21504
	ds_read_b128 v[214:217], v149 offset:22528
	ds_read_b128 v[218:221], v149 offset:23552
	global_load_lds_dwordx4 v[166:167], off
	s_add_i32 m0, s78, 0x2000
	s_add_u32 s78, s52, 0x80000
	v_lshl_add_u64 v[206:207], s[52:53], 0, v[134:135]
	s_addc_u32 s79, s53, 0
	s_add_i32 s80, s70, s33
	global_load_lds_dwordx4 v[206:207], off
	v_lshl_add_u64 v[222:223], s[78:79], 0, v[130:131]
	s_mov_b32 m0, s80
	v_lshl_add_u64 v[224:225], s[54:55], 0, v[132:133]
	global_load_lds_dwordx4 v[222:223], off
	v_lshl_add_u64 v[222:223], s[78:79], 0, v[134:135]
	s_add_i32 m0, s80, 0x2000
	s_nop 0
	global_load_lds_dwordx4 v[222:223], off
	v_lshl_add_u64 v[222:223], s[54:55], 0, v[128:129]
	s_mov_b32 m0, s43
	s_nop 0
	global_load_lds_dwordx4 v[222:223], off
	s_mov_b32 m0, s62
	s_nop 0
	global_load_lds_dwordx4 v[224:225], off
	s_waitcnt vmcnt(8)
	s_waitcnt lgkmcnt(0)
	s_barrier
; #define PG8_STAGE(bufoff, gbase, voff) do { _Pragma("unroll") for (int _i = 0; _i < 2; ++_i) \
;         __builtin_amdgcn_global_load_lds((const unsigned*)((const char*)(gbase) + (voff)[_i]), (PG8_LAS unsigned*)(lds + (bufoff) + ldsw + _i * 8192), 16, 0, 0); } while (0)
; #define PG8_LDA(dst, b, h) do { _Pragma("unroll") for (int m = 0; m < 4; ++m) _Pragma("unroll") for (int k = 0; k < 2; ++k) dst[m][k] = *(const PG8_LAS bf16x8*)(lds + PG8_SA(b, h) + aoff + m * 2048 + k * 1024); } while (0)
; #define PG8_LDB(dst, b, h) do { _Pragma("unroll") for (int n = 0; n < 2; ++n) _Pragma("unroll") for (int k = 0; k < 2; ++k) dst[n][k] = *(const PG8_LAS bf16x8*)(lds + PG8_SB(b, h) + boff + n * 2048 + k * 1024); } while (0)
; #define PG8_MMA(ai, bj, At, Bt) do { __builtin_amdgcn_s_setprio(1); _Pragma("unroll") for (int m = 0; m < 4; ++m) _Pragma("unroll") for (int n = 0; n < 2; ++n) _Pragma("unroll") for (int k = 0; k < 2; ++k) \
;         acc[ai][bj][m][n] = __builtin_amdgcn_mfma_f32_16x16x32_bf16(Bt[n][k], At[m][k], acc[ai][bj][m][n], 0, 0, 0); __builtin_amdgcn_s_setprio(0); } while (0)
; #define PG8_WAIT_V(n) asm volatile("s_waitcnt vmcnt(" #n ")" ::: "memory")
; #define PG8_WAIT_L(n) asm volatile("s_waitcnt lgkmcnt(" #n ")" ::: "memory")
; #define PG8_BAR __builtin_amdgcn_s_barrier()
; #define PG8_SCHED __builtin_amdgcn_sched_barrier(0)
; template <class Epi, class Sched, bool ALIGN_EPI = false, bool SP2 = false>
; __device__ __forceinline__ void gemm_phase(PG8_LAS unsigned char* lds, const Gemm g, const Sched& S, const Epi& E) {
;     ...
;             PG8_WAIT_V(8); PG8_WAIT_L(0); PG8_BAR; PG8_MMA(1, 0, At, B0); PG8_MMA(1, 1, At, B1); PG8_BAR; PG8_SCHED;
;             PG8_LDB(B0, 1, 0); PG8_LDB(B1, 1, 1); PG8_SCHED; PG8_LDA(At, 1, 0); PG8_STAGE(PG8_SA(0, 1), a2 + hstepA, voffA);
;             PG8_WAIT_V(8); PG8_WAIT_L(0); PG8_BAR; PG8_MMA(0, 0, At, B0); PG8_MMA(0, 1, At, B1); PG8_BAR; PG8_SCHED;
	s_setprio 1
	s_waitcnt lgkmcnt(0)
	v_mfma_f32_16x16x32_bf16 v[60:63], v[150:153], v[186:189], v[60:63]
	v_mfma_f32_16x16x32_bf16 v[56:59], v[158:161], v[186:189], v[56:59]
	v_mfma_f32_16x16x32_bf16 v[52:55], v[150:153], v[194:197], v[52:55]
	v_mfma_f32_16x16x32_bf16 v[48:51], v[158:161], v[194:197], v[48:51]
	v_mfma_f32_16x16x32_bf16 v[36:39], v[150:153], v[202:205], v[36:39]
	v_mfma_f32_16x16x32_bf16 v[32:35], v[158:161], v[202:205], v[32:35]
	v_mfma_f32_16x16x32_bf16 v[20:23], v[150:153], v[214:217], v[20:23]
	v_mfma_f32_16x16x32_bf16 v[16:19], v[158:161], v[214:217], v[16:19]
	v_mfma_f32_16x16x32_bf16 v[60:63], v[154:157], v[190:193], v[60:63]
	v_mfma_f32_16x16x32_bf16 v[56:59], v[162:165], v[190:193], v[56:59]
	v_mfma_f32_16x16x32_bf16 v[52:55], v[154:157], v[198:201], v[52:55]
	v_mfma_f32_16x16x32_bf16 v[48:51], v[162:165], v[198:201], v[48:51]
	v_mfma_f32_16x16x32_bf16 v[36:39], v[154:157], v[210:213], v[36:39]
	v_mfma_f32_16x16x32_bf16 v[32:35], v[162:165], v[210:213], v[32:35]
	v_mfma_f32_16x16x32_bf16 v[20:23], v[154:157], v[218:221], v[20:23]
	v_mfma_f32_16x16x32_bf16 v[16:19], v[162:165], v[218:221], v[16:19]
	s_setprio 0
	s_setprio 1
	v_mfma_f32_16x16x32_bf16 v[44:47], v[170:173], v[186:189], v[44:47]
	v_mfma_f32_16x16x32_bf16 v[40:43], v[178:181], v[186:189], v[40:43]
	v_mfma_f32_16x16x32_bf16 v[28:31], v[170:173], v[194:197], v[28:31]
	v_mfma_f32_16x16x32_bf16 v[24:27], v[178:181], v[194:197], v[24:27]
	v_mfma_f32_16x16x32_bf16 v[12:15], v[170:173], v[202:205], v[12:15]
	v_mfma_f32_16x16x32_bf16 v[8:11], v[178:181], v[202:205], v[8:11]
	v_mfma_f32_16x16x32_bf16 v[4:7], v[170:173], v[214:217], v[4:7]
	v_mfma_f32_16x16x32_bf16 v[0:3], v[178:181], v[214:217], v[0:3]
	v_mfma_f32_16x16x32_bf16 v[44:47], v[174:177], v[190:193], v[44:47]
	v_mfma_f32_16x16x32_bf16 v[40:43], v[182:185], v[190:193], v[40:43]
	v_mfma_f32_16x16x32_bf16 v[28:31], v[174:177], v[198:201], v[28:31]
	v_mfma_f32_16x16x32_bf16 v[24:27], v[182:185], v[198:201], v[24:27]
	v_mfma_f32_16x16x32_bf16 v[12:15], v[174:177], v[210:213], v[12:15]
	v_mfma_f32_16x16x32_bf16 v[8:11], v[182:185], v[210:213], v[8:11]
	v_mfma_f32_16x16x32_bf16 v[4:7], v[174:177], v[218:221], v[4:7]
	v_mfma_f32_16x16x32_bf16 v[0:3], v[182:185], v[218:221], v[0:3]
	s_setprio 0
	s_barrier
	s_add_i32 s78, 0, 0x18000
	s_add_i32 s79, 0, 0x1c000
	v_add_u32_e32 v162, s78, v145
	v_add_u32_e32 v169, s79, v145
	ds_read_b128 v[150:153], v162
	ds_read_b128 v[154:157], v162 offset:1024
	ds_read_b128 v[158:161], v162 offset:2048
	ds_read_b128 v[162:165], v162 offset:3072
	ds_read_b128 v[170:173], v169
	ds_read_b128 v[174:177], v169 offset:1024
	ds_read_b128 v[178:181], v169 offset:2048
	ds_read_b128 v[182:185], v169 offset:3072
	s_add_u32 s54, s54, 0x80000
	s_addc_u32 s55, s55, 0
	s_mov_b32 m0, s63
	v_lshl_add_u64 v[226:227], s[54:55], 0, v[128:129]
	ds_read_b128 v[186:189], v149 offset:32768
	ds_read_b128 v[190:193], v149 offset:33792
	ds_read_b128 v[194:197], v149 offset:34816
	ds_read_b128 v[198:201], v149 offset:35840
	ds_read_b128 v[202:205], v149 offset:36864
	ds_read_b128 v[210:213], v149 offset:37888
	ds_read_b128 v[214:217], v149 offset:38912
	ds_read_b128 v[218:221], v149 offset:39936
	global_load_lds_dwordx4 v[226:227], off
	v_lshl_add_u64 v[226:227], s[54:55], 0, v[132:133]
	s_mov_b32 m0, s64
	s_nop 0
	global_load_lds_dwordx4 v[226:227], off
	s_waitcnt vmcnt(8)
	s_waitcnt lgkmcnt(0)
	s_barrier
	s_setprio 1
	s_waitcnt lgkmcnt(0)
	v_mfma_f32_16x16x32_bf16 v[124:127], v[150:153], v[186:189], v[124:127]
	v_mfma_f32_16x16x32_bf16 v[120:123], v[158:161], v[186:189], v[120:123]
	v_mfma_f32_16x16x32_bf16 v[116:119], v[150:153], v[194:197], v[116:119]
	v_mfma_f32_16x16x32_bf16 v[112:115], v[158:161], v[194:197], v[112:115]
	v_mfma_f32_16x16x32_bf16 v[100:103], v[150:153], v[202:205], v[100:103]
	v_mfma_f32_16x16x32_bf16 v[96:99], v[158:161], v[202:205], v[96:99]
	v_mfma_f32_16x16x32_bf16 v[84:87], v[150:153], v[214:217], v[84:87]
	v_mfma_f32_16x16x32_bf16 v[80:83], v[158:161], v[214:217], v[80:83]
	v_mfma_f32_16x16x32_bf16 v[124:127], v[154:157], v[190:193], v[124:127]
	v_mfma_f32_16x16x32_bf16 v[120:123], v[162:165], v[190:193], v[120:123]
	v_mfma_f32_16x16x32_bf16 v[116:119], v[154:157], v[198:201], v[116:119]
	v_mfma_f32_16x16x32_bf16 v[112:115], v[162:165], v[198:201], v[112:115]
	v_mfma_f32_16x16x32_bf16 v[100:103], v[154:157], v[210:213], v[100:103]
	v_mfma_f32_16x16x32_bf16 v[96:99], v[162:165], v[210:213], v[96:99]
	v_mfma_f32_16x16x32_bf16 v[84:87], v[154:157], v[218:221], v[84:87]
	v_mfma_f32_16x16x32_bf16 v[80:83], v[162:165], v[218:221], v[80:83]
	s_setprio 0
	s_setprio 1
	v_mfma_f32_16x16x32_bf16 v[108:111], v[170:173], v[186:189], v[108:111]
	v_mfma_f32_16x16x32_bf16 v[104:107], v[178:181], v[186:189], v[104:107]
	v_mfma_f32_16x16x32_bf16 v[92:95], v[170:173], v[194:197], v[92:95]
	v_mfma_f32_16x16x32_bf16 v[88:91], v[178:181], v[194:197], v[88:91]
	v_mfma_f32_16x16x32_bf16 v[76:79], v[170:173], v[202:205], v[76:79]
	v_mfma_f32_16x16x32_bf16 v[72:75], v[178:181], v[202:205], v[72:75]
	v_mfma_f32_16x16x32_bf16 v[68:71], v[170:173], v[214:217], v[68:71]
	v_mfma_f32_16x16x32_bf16 v[64:67], v[178:181], v[214:217], v[64:67]
	v_mfma_f32_16x16x32_bf16 v[108:111], v[174:177], v[190:193], v[108:111]
	v_mfma_f32_16x16x32_bf16 v[104:107], v[182:185], v[190:193], v[104:107]
	v_mfma_f32_16x16x32_bf16 v[92:95], v[174:177], v[198:201], v[92:95]
	v_mfma_f32_16x16x32_bf16 v[88:91], v[182:185], v[198:201], v[88:91]
	v_mfma_f32_16x16x32_bf16 v[76:79], v[174:177], v[210:213], v[76:79]
	v_mfma_f32_16x16x32_bf16 v[72:75], v[182:185], v[210:213], v[72:75]
	v_mfma_f32_16x16x32_bf16 v[68:71], v[174:177], v[218:221], v[68:71]
	v_mfma_f32_16x16x32_bf16 v[64:67], v[182:185], v[218:221], v[64:67]
	s_setprio 0
	s_barrier
; #define PG8_STAGE(bufoff, gbase, voff) do { _Pragma("unroll") for (int _i = 0; _i < 2; ++_i) \
;         __builtin_amdgcn_global_load_lds((const unsigned*)((const char*)(gbase) + (voff)[_i]), (PG8_LAS unsigned*)(lds + (bufoff) + ldsw + _i * 8192), 16, 0, 0); } while (0)
; #define PG8_LDA(dst, b, h) do { _Pragma("unroll") for (int m = 0; m < 4; ++m) _Pragma("unroll") for (int k = 0; k < 2; ++k) dst[m][k] = *(const PG8_LAS bf16x8*)(lds + PG8_SA(b, h) + aoff + m * 2048 + k * 1024); } while (0)
; #define PG8_MMA(ai, bj, At, Bt) do { __builtin_amdgcn_s_setprio(1); _Pragma("unroll") for (int m = 0; m < 4; ++m) _Pragma("unroll") for (int n = 0; n < 2; ++n) _Pragma("unroll") for (int k = 0; k < 2; ++k) \
;         acc[ai][bj][m][n] = __builtin_amdgcn_mfma_f32_16x16x32_bf16(Bt[n][k], At[m][k], acc[ai][bj][m][n], 0, 0, 0); __builtin_amdgcn_s_setprio(0); } while (0)
; #define PG8_WAIT_V(n) asm volatile("s_waitcnt vmcnt(" #n ")" ::: "memory")
; #define PG8_WAIT_L(n) asm volatile("s_waitcnt lgkmcnt(" #n ")" ::: "memory")
; #define PG8_BAR __builtin_amdgcn_s_barrier()
; #define PG8_SCHED __builtin_amdgcn_sched_barrier(0)
; template <class Epi, class Sched, bool ALIGN_EPI = false, bool SP2 = false>
; __device__ __forceinline__ void gemm_phase(PG8_LAS unsigned char* lds, const Gemm g, const Sched& S, const Epi& E) {
;     ...
;         for (int t = 0; t < nt; t += 2) {
;     ...
;             PG8_LDA(At, 1, 1); PG8_STAGE(PG8_SB(1, 0), b3, voffB); PG8_STAGE(PG8_SB(1, 1), b3 + hstepB, voffB); PG8_STAGE(PG8_SA(1, 0), a3, voffA);
;             PG8_WAIT_V(8); PG8_WAIT_L(0); PG8_BAR; PG8_MMA(1, 0, At, B0); PG8_MMA(1, 1, At, B1); PG8_BAR; PG8_SCHED;
	s_add_i32 s54, s78, s33
	v_lshl_add_u64 v[166:167], v[166:167], 0, s[30:31]
	s_mov_b32 m0, s54
	ds_read_b128 v[186:189], v149 offset:49152
	ds_read_b128 v[190:193], v149 offset:50176
	ds_read_b128 v[194:197], v149 offset:51200
	ds_read_b128 v[198:201], v149 offset:52224
	ds_read_b128 v[202:205], v149 offset:53248
	ds_read_b128 v[210:213], v149 offset:54272
	ds_read_b128 v[214:217], v149 offset:55296
	ds_read_b128 v[218:221], v149 offset:56320
	global_load_lds_dwordx4 v[166:167], off
	s_add_i32 m0, s54, 0x2000
	s_add_u32 s52, s52, 0x80080
	v_lshl_add_u64 v[166:167], v[206:207], 0, s[30:31]
	s_addc_u32 s53, s53, 0
	s_add_i32 s54, s79, s33
	global_load_lds_dwordx4 v[166:167], off
	v_lshl_add_u64 v[166:167], s[52:53], 0, v[130:131]
	s_mov_b32 m0, s54
	s_nop 0
	global_load_lds_dwordx4 v[166:167], off
	v_lshl_add_u64 v[166:167], s[52:53], 0, v[134:135]
	s_add_i32 m0, s54, 0x2000
	s_nop 0
	global_load_lds_dwordx4 v[166:167], off
	v_lshl_add_u64 v[166:167], v[222:223], 0, s[30:31]
	s_mov_b32 m0, s66
	s_nop 0
	global_load_lds_dwordx4 v[166:167], off
	v_lshl_add_u64 v[166:167], v[224:225], 0, s[30:31]
	s_mov_b32 m0, s67
	s_nop 0
	global_load_lds_dwordx4 v[166:167], off
	s_waitcnt vmcnt(8)
	s_waitcnt lgkmcnt(0)
	s_barrier
	s_setprio 1
	s_waitcnt lgkmcnt(0)
	v_mfma_f32_16x16x32_bf16 v[60:63], v[150:153], v[186:189], v[60:63]
	v_mfma_f32_16x16x32_bf16 v[56:59], v[158:161], v[186:189], v[56:59]
	v_mfma_f32_16x16x32_bf16 v[52:55], v[150:153], v[194:197], v[52:55]
	v_mfma_f32_16x16x32_bf16 v[48:51], v[158:161], v[194:197], v[48:51]
	v_mfma_f32_16x16x32_bf16 v[36:39], v[150:153], v[202:205], v[36:39]
	v_mfma_f32_16x16x32_bf16 v[32:35], v[158:161], v[202:205], v[32:35]
	v_mfma_f32_16x16x32_bf16 v[20:23], v[150:153], v[214:217], v[20:23]
	v_mfma_f32_16x16x32_bf16 v[16:19], v[158:161], v[214:217], v[16:19]
	v_mfma_f32_16x16x32_bf16 v[60:63], v[154:157], v[190:193], v[60:63]
	v_mfma_f32_16x16x32_bf16 v[56:59], v[162:165], v[190:193], v[56:59]
	v_mfma_f32_16x16x32_bf16 v[52:55], v[154:157], v[198:201], v[52:55]
	v_mfma_f32_16x16x32_bf16 v[48:51], v[162:165], v[198:201], v[48:51]
	v_mfma_f32_16x16x32_bf16 v[36:39], v[154:157], v[210:213], v[36:39]
	v_mfma_f32_16x16x32_bf16 v[32:35], v[162:165], v[210:213], v[32:35]
	v_mfma_f32_16x16x32_bf16 v[20:23], v[154:157], v[218:221], v[20:23]
	v_mfma_f32_16x16x32_bf16 v[16:19], v[162:165], v[218:221], v[16:19]
	s_setprio 0
	s_setprio 1
	v_mfma_f32_16x16x32_bf16 v[44:47], v[170:173], v[186:189], v[44:47]
	v_mfma_f32_16x16x32_bf16 v[40:43], v[178:181], v[186:189], v[40:43]
	v_mfma_f32_16x16x32_bf16 v[28:31], v[170:173], v[194:197], v[28:31]
	v_mfma_f32_16x16x32_bf16 v[24:27], v[178:181], v[194:197], v[24:27]
	v_mfma_f32_16x16x32_bf16 v[12:15], v[170:173], v[202:205], v[12:15]
	v_mfma_f32_16x16x32_bf16 v[8:11], v[178:181], v[202:205], v[8:11]
	v_mfma_f32_16x16x32_bf16 v[4:7], v[170:173], v[214:217], v[4:7]
	v_mfma_f32_16x16x32_bf16 v[0:3], v[178:181], v[214:217], v[0:3]
	v_mfma_f32_16x16x32_bf16 v[44:47], v[174:177], v[190:193], v[44:47]
	v_mfma_f32_16x16x32_bf16 v[40:43], v[182:185], v[190:193], v[40:43]
	v_mfma_f32_16x16x32_bf16 v[28:31], v[174:177], v[198:201], v[28:31]
	v_mfma_f32_16x16x32_bf16 v[24:27], v[182:185], v[198:201], v[24:27]
	v_mfma_f32_16x16x32_bf16 v[12:15], v[174:177], v[210:213], v[12:15]
	v_mfma_f32_16x16x32_bf16 v[8:11], v[182:185], v[210:213], v[8:11]
	v_mfma_f32_16x16x32_bf16 v[4:7], v[174:177], v[218:221], v[4:7]
	v_mfma_f32_16x16x32_bf16 v[0:3], v[182:185], v[218:221], v[0:3]
	s_setprio 0
	s_add_i32 s77, s77, 2
	s_add_u32 s50, s50, 0x100
	s_addc_u32 s51, s51, 0
	s_add_u32 s75, s75, 0x100
	s_addc_u32 s76, s76, 0
	s_cmp_gt_u32 s77, 29
	s_barrier
	s_cbranch_scc0 .LBB0_732
	s_and_b64 vcc, exec, s[22:23]
	s_cbranch_vccz .LBB0_735
	s_barrier

; #define PG8_STAGE(bufoff, gbase, voff) do { _Pragma("unroll") for (int _i = 0; _i < 2; ++_i) \
;         __builtin_amdgcn_global_load_lds((const unsigned*)((const char*)(gbase) + (voff)[_i]), (PG8_LAS unsigned*)(lds + (bufoff) + ldsw + _i * 8192), 16, 0, 0); } while (0)
; #define PG8_LDA(dst, b, h) do { _Pragma("unroll") for (int m = 0; m < 4; ++m) _Pragma("unroll") for (int k = 0; k < 2; ++k) dst[m][k] = *(const PG8_LAS bf16x8*)(lds + PG8_SA(b, h) + aoff + m * 2048 + k * 1024); } while (0)
; #define PG8_LDB(dst, b, h) do { _Pragma("unroll") for (int n = 0; n < 2; ++n) _Pragma("unroll") for (int k = 0; k < 2; ++k) dst[n][k] = *(const PG8_LAS bf16x8*)(lds + PG8_SB(b, h) + boff + n * 2048 + k * 1024); } while (0)
; #define PG8_MMA(ai, bj, At, Bt) do { __builtin_amdgcn_s_setprio(1); _Pragma("unroll") for (int m = 0; m < 4; ++m) _Pragma("unroll") for (int n = 0; n < 2; ++n) _Pragma("unroll") for (int k = 0; k < 2; ++k) \
;         acc[ai][bj][m][n] = __builtin_amdgcn_mfma_f32_16x16x32_bf16(Bt[n][k], At[m][k], acc[ai][bj][m][n], 0, 0, 0); __builtin_amdgcn_s_setprio(0); } while (0)
; #define PG8_WAIT_V(n) asm volatile("s_waitcnt vmcnt(" #n ")" ::: "memory")
; #define PG8_WAIT_L(n) asm volatile("s_waitcnt lgkmcnt(" #n ")" ::: "memory")
; #define PG8_BAR __builtin_amdgcn_s_barrier()
; #define PG8_SCHED __builtin_amdgcn_sched_barrier(0)
; template <class Epi, class Sched, bool ALIGN_EPI = false, bool SP2 = false>
; __device__ __forceinline__ void gemm_phase(PG8_LAS unsigned char* lds, const Gemm g, const Sched& S, const Epi& E) {
;     ...
;             PG8_LDB(B0, 0, 0); PG8_LDB(B1, 0, 1); PG8_SCHED; PG8_LDA(At, 0, 0); PG8_STAGE(PG8_SA(1, 1), a1 + hstepA, voffA);
;             PG8_WAIT_V(8); PG8_WAIT_L(0); PG8_BAR; PG8_MMA(0, 0, At, B0); PG8_MMA(0, 1, At, B1); PG8_BAR; PG8_SCHED;
;             PG8_LDA(At, 0, 1); PG8_STAGE(PG8_SB(0, 0), b2, voffB); PG8_STAGE(PG8_SB(0, 1), b2 + hstepB, voffB); PG8_STAGE(PG8_SA(0, 0), a2, voffA);
.LBB0_866:
	ds_read_b128 v[150:153], v147
	ds_read_b128 v[154:157], v147 offset:1024
	ds_read_b128 v[158:161], v147 offset:2048
	ds_read_b128 v[162:165], v147 offset:3072
	ds_read_b128 v[170:173], v148
	ds_read_b128 v[174:177], v148 offset:1024
	ds_read_b128 v[178:181], v148 offset:2048
	ds_read_b128 v[182:185], v148 offset:3072
	s_add_u32 s52, s50, 0xfff80080
	s_addc_u32 s53, s51, -1
	s_cmp_eq_u32 s75, 28
	s_cselect_b32 s55, s37, s53
	s_cselect_b32 s54, s71, s52
	s_cselect_b32 s53, s35, s74
	s_cselect_b32 s52, s72, s73
	v_lshl_add_u64 v[166:167], s[50:51], 0, v[136:137]
	s_add_i32 m0, s45, 0xc000
	ds_read_b128 v[186:189], v149
	ds_read_b128 v[190:193], v149 offset:1024
	ds_read_b128 v[194:197], v149 offset:2048
	ds_read_b128 v[198:201], v149 offset:3072
	ds_read_b128 v[202:205], v149 offset:4096
	ds_read_b128 v[210:213], v149 offset:5120
	ds_read_b128 v[214:217], v149 offset:6144
	ds_read_b128 v[218:221], v149 offset:7168
	global_load_lds_dwordx4 v[166:167], off
	v_lshl_add_u64 v[166:167], s[50:51], 0, v[138:139]
	s_add_i32 m0, s45, 0xe000
	s_nop 0
	global_load_lds_dwordx4 v[166:167], off
	s_waitcnt vmcnt(8)
	s_waitcnt lgkmcnt(0)
	s_barrier
	s_setprio 1
	s_waitcnt lgkmcnt(0)
	v_mfma_f32_16x16x32_bf16 v[124:127], v[150:153], v[186:189], v[124:127]
	v_mfma_f32_16x16x32_bf16 v[120:123], v[158:161], v[186:189], v[120:123]
	v_mfma_f32_16x16x32_bf16 v[108:111], v[150:153], v[194:197], v[108:111]
	v_mfma_f32_16x16x32_bf16 v[104:107], v[158:161], v[194:197], v[104:107]
	v_mfma_f32_16x16x32_bf16 v[92:95], v[150:153], v[202:205], v[92:95]
	v_mfma_f32_16x16x32_bf16 v[88:91], v[158:161], v[202:205], v[88:91]
	v_mfma_f32_16x16x32_bf16 v[76:79], v[150:153], v[214:217], v[76:79]
	v_mfma_f32_16x16x32_bf16 v[72:75], v[158:161], v[214:217], v[72:75]
	v_mfma_f32_16x16x32_bf16 v[124:127], v[154:157], v[190:193], v[124:127]
	v_mfma_f32_16x16x32_bf16 v[120:123], v[162:165], v[190:193], v[120:123]
	v_mfma_f32_16x16x32_bf16 v[108:111], v[154:157], v[198:201], v[108:111]
	v_mfma_f32_16x16x32_bf16 v[104:107], v[162:165], v[198:201], v[104:107]
	v_mfma_f32_16x16x32_bf16 v[92:95], v[154:157], v[210:213], v[92:95]
	v_mfma_f32_16x16x32_bf16 v[88:91], v[162:165], v[210:213], v[88:91]
	v_mfma_f32_16x16x32_bf16 v[76:79], v[154:157], v[218:221], v[76:79]
	v_mfma_f32_16x16x32_bf16 v[72:75], v[162:165], v[218:221], v[72:75]
	s_setprio 0
	s_setprio 1
	v_mfma_f32_16x16x32_bf16 v[116:119], v[170:173], v[186:189], v[116:119]
	v_mfma_f32_16x16x32_bf16 v[112:115], v[178:181], v[186:189], v[112:115]
	v_mfma_f32_16x16x32_bf16 v[100:103], v[170:173], v[194:197], v[100:103]
	v_mfma_f32_16x16x32_bf16 v[96:99], v[178:181], v[194:197], v[96:99]
	v_mfma_f32_16x16x32_bf16 v[84:87], v[170:173], v[202:205], v[84:87]
	v_mfma_f32_16x16x32_bf16 v[80:83], v[178:181], v[202:205], v[80:83]
	v_mfma_f32_16x16x32_bf16 v[68:71], v[170:173], v[214:217], v[68:71]
	v_mfma_f32_16x16x32_bf16 v[64:67], v[178:181], v[214:217], v[64:67]
	v_mfma_f32_16x16x32_bf16 v[116:119], v[174:177], v[190:193], v[116:119]
	v_mfma_f32_16x16x32_bf16 v[112:115], v[182:185], v[190:193], v[112:115]
	v_mfma_f32_16x16x32_bf16 v[100:103], v[174:177], v[198:201], v[100:103]
	v_mfma_f32_16x16x32_bf16 v[96:99], v[182:185], v[198:201], v[96:99]
	v_mfma_f32_16x16x32_bf16 v[84:87], v[174:177], v[210:213], v[84:87]
	v_mfma_f32_16x16x32_bf16 v[80:83], v[182:185], v[210:213], v[80:83]
	v_mfma_f32_16x16x32_bf16 v[68:71], v[174:177], v[218:221], v[68:71]
	v_mfma_f32_16x16x32_bf16 v[64:67], v[182:185], v[218:221], v[64:67]
	s_setprio 0
	s_barrier
	s_add_i32 s76, s67, s3
	v_lshl_add_u64 v[166:167], s[52:53], 0, v[132:133]
	s_mov_b32 m0, s76
	ds_read_b128 v[186:189], v149 offset:16384
	ds_read_b128 v[190:193], v149 offset:17408
	ds_read_b128 v[194:197], v149 offset:18432
	ds_read_b128 v[198:201], v149 offset:19456
	ds_read_b128 v[202:205], v149 offset:20480
	ds_read_b128 v[210:213], v149 offset:21504
	ds_read_b128 v[214:217], v149 offset:22528
	ds_read_b128 v[218:221], v149 offset:23552
	global_load_lds_dwordx4 v[166:167], off
	s_add_i32 m0, s76, 0x2000
	s_add_u32 s76, s52, 0x80000
	v_lshl_add_u64 v[206:207], s[52:53], 0, v[128:129]
	s_addc_u32 s77, s53, 0
	s_add_i32 s78, s68, s3
	global_load_lds_dwordx4 v[206:207], off
	v_lshl_add_u64 v[222:223], s[76:77], 0, v[132:133]
	s_mov_b32 m0, s78
	v_lshl_add_u64 v[224:225], s[54:55], 0, v[130:131]
	global_load_lds_dwordx4 v[222:223], off
	v_lshl_add_u64 v[222:223], s[76:77], 0, v[128:129]
	s_add_i32 m0, s78, 0x2000
	s_nop 0
	global_load_lds_dwordx4 v[222:223], off
	v_lshl_add_u64 v[222:223], s[54:55], 0, v[134:135]
	s_mov_b32 m0, s45
	s_nop 0
	global_load_lds_dwordx4 v[222:223], off
	s_mov_b32 m0, s60
	s_nop 0
	global_load_lds_dwordx4 v[224:225], off
	s_waitcnt vmcnt(8)
	s_waitcnt lgkmcnt(0)
	s_barrier
; #define PG8_STAGE(bufoff, gbase, voff) do { _Pragma("unroll") for (int _i = 0; _i < 2; ++_i) \
;         __builtin_amdgcn_global_load_lds((const unsigned*)((const char*)(gbase) + (voff)[_i]), (PG8_LAS unsigned*)(lds + (bufoff) + ldsw + _i * 8192), 16, 0, 0); } while (0)
; #define PG8_LDA(dst, b, h) do { _Pragma("unroll") for (int m = 0; m < 4; ++m) _Pragma("unroll") for (int k = 0; k < 2; ++k) dst[m][k] = *(const PG8_LAS bf16x8*)(lds + PG8_SA(b, h) + aoff + m * 2048 + k * 1024); } while (0)
; #define PG8_LDB(dst, b, h) do { _Pragma("unroll") for (int n = 0; n < 2; ++n) _Pragma("unroll") for (int k = 0; k < 2; ++k) dst[n][k] = *(const PG8_LAS bf16x8*)(lds + PG8_SB(b, h) + boff + n * 2048 + k * 1024); } while (0)
; #define PG8_MMA(ai, bj, At, Bt) do { __builtin_amdgcn_s_setprio(1); _Pragma("unroll") for (int m = 0; m < 4; ++m) _Pragma("unroll") for (int n = 0; n < 2; ++n) _Pragma("unroll") for (int k = 0; k < 2; ++k) \
;         acc[ai][bj][m][n] = __builtin_amdgcn_mfma_f32_16x16x32_bf16(Bt[n][k], At[m][k], acc[ai][bj][m][n], 0, 0, 0); __builtin_amdgcn_s_setprio(0); } while (0)
; #define PG8_WAIT_V(n) asm volatile("s_waitcnt vmcnt(" #n ")" ::: "memory")
; #define PG8_WAIT_L(n) asm volatile("s_waitcnt lgkmcnt(" #n ")" ::: "memory")
; #define PG8_BAR __builtin_amdgcn_s_barrier()
; #define PG8_SCHED __builtin_amdgcn_sched_barrier(0)
; template <class Epi, class Sched, bool ALIGN_EPI = false, bool SP2 = false>
; __device__ __forceinline__ void gemm_phase(PG8_LAS unsigned char* lds, const Gemm g, const Sched& S, const Epi& E) {
;     ...
;             PG8_WAIT_V(8); PG8_WAIT_L(0); PG8_BAR; PG8_MMA(1, 0, At, B0); PG8_MMA(1, 1, At, B1); PG8_BAR; PG8_SCHED;
;             PG8_LDB(B0, 1, 0); PG8_LDB(B1, 1, 1); PG8_SCHED; PG8_LDA(At, 1, 0); PG8_STAGE(PG8_SA(0, 1), a2 + hstepA, voffA);
;             PG8_WAIT_V(8); PG8_WAIT_L(0); PG8_BAR; PG8_MMA(0, 0, At, B0); PG8_MMA(0, 1, At, B1); PG8_BAR; PG8_SCHED;
	s_setprio 1
	s_waitcnt lgkmcnt(0)
	v_mfma_f32_16x16x32_bf16 v[60:63], v[150:153], v[186:189], v[60:63]
	v_mfma_f32_16x16x32_bf16 v[56:59], v[158:161], v[186:189], v[56:59]
	v_mfma_f32_16x16x32_bf16 v[44:47], v[150:153], v[194:197], v[44:47]
	v_mfma_f32_16x16x32_bf16 v[40:43], v[158:161], v[194:197], v[40:43]
	v_mfma_f32_16x16x32_bf16 v[28:31], v[150:153], v[202:205], v[28:31]
	v_mfma_f32_16x16x32_bf16 v[24:27], v[158:161], v[202:205], v[24:27]
	v_mfma_f32_16x16x32_bf16 v[12:15], v[150:153], v[214:217], v[12:15]
	v_mfma_f32_16x16x32_bf16 v[8:11], v[158:161], v[214:217], v[8:11]
	v_mfma_f32_16x16x32_bf16 v[60:63], v[154:157], v[190:193], v[60:63]
	v_mfma_f32_16x16x32_bf16 v[56:59], v[162:165], v[190:193], v[56:59]
	v_mfma_f32_16x16x32_bf16 v[44:47], v[154:157], v[198:201], v[44:47]
	v_mfma_f32_16x16x32_bf16 v[40:43], v[162:165], v[198:201], v[40:43]
	v_mfma_f32_16x16x32_bf16 v[28:31], v[154:157], v[210:213], v[28:31]
	v_mfma_f32_16x16x32_bf16 v[24:27], v[162:165], v[210:213], v[24:27]
	v_mfma_f32_16x16x32_bf16 v[12:15], v[154:157], v[218:221], v[12:15]
	v_mfma_f32_16x16x32_bf16 v[8:11], v[162:165], v[218:221], v[8:11]
	s_setprio 0
	s_setprio 1
	v_mfma_f32_16x16x32_bf16 v[52:55], v[170:173], v[186:189], v[52:55]
	v_mfma_f32_16x16x32_bf16 v[48:51], v[178:181], v[186:189], v[48:51]
	v_mfma_f32_16x16x32_bf16 v[36:39], v[170:173], v[194:197], v[36:39]
	v_mfma_f32_16x16x32_bf16 v[32:35], v[178:181], v[194:197], v[32:35]
	v_mfma_f32_16x16x32_bf16 v[20:23], v[170:173], v[202:205], v[20:23]
	v_mfma_f32_16x16x32_bf16 v[16:19], v[178:181], v[202:205], v[16:19]
	v_mfma_f32_16x16x32_bf16 v[4:7], v[170:173], v[214:217], v[4:7]
	v_mfma_f32_16x16x32_bf16 v[0:3], v[178:181], v[214:217], v[0:3]
	v_mfma_f32_16x16x32_bf16 v[52:55], v[174:177], v[190:193], v[52:55]
	v_mfma_f32_16x16x32_bf16 v[48:51], v[182:185], v[190:193], v[48:51]
	v_mfma_f32_16x16x32_bf16 v[36:39], v[174:177], v[198:201], v[36:39]
	v_mfma_f32_16x16x32_bf16 v[32:35], v[182:185], v[198:201], v[32:35]
	v_mfma_f32_16x16x32_bf16 v[20:23], v[174:177], v[210:213], v[20:23]
	v_mfma_f32_16x16x32_bf16 v[16:19], v[182:185], v[210:213], v[16:19]
	v_mfma_f32_16x16x32_bf16 v[4:7], v[174:177], v[218:221], v[4:7]
	v_mfma_f32_16x16x32_bf16 v[0:3], v[182:185], v[218:221], v[0:3]
	s_setprio 0
	s_barrier
	s_add_i32 s76, 0, 0x18000
	s_add_i32 s77, 0, 0x1c000
	v_add_u32_e32 v162, s76, v145
	v_add_u32_e32 v169, s77, v145
	ds_read_b128 v[150:153], v162
	ds_read_b128 v[154:157], v162 offset:1024
	ds_read_b128 v[158:161], v162 offset:2048
	ds_read_b128 v[162:165], v162 offset:3072
	ds_read_b128 v[170:173], v169
	ds_read_b128 v[174:177], v169 offset:1024
	ds_read_b128 v[178:181], v169 offset:2048
	ds_read_b128 v[182:185], v169 offset:3072
	s_add_u32 s54, s54, 0x80000
	s_addc_u32 s55, s55, 0
	s_mov_b32 m0, s61
	v_lshl_add_u64 v[226:227], s[54:55], 0, v[134:135]
	ds_read_b128 v[186:189], v149 offset:32768
	ds_read_b128 v[190:193], v149 offset:33792
	ds_read_b128 v[194:197], v149 offset:34816
	ds_read_b128 v[198:201], v149 offset:35840
	ds_read_b128 v[202:205], v149 offset:36864
	ds_read_b128 v[210:213], v149 offset:37888
	ds_read_b128 v[214:217], v149 offset:38912
	ds_read_b128 v[218:221], v149 offset:39936
	global_load_lds_dwordx4 v[226:227], off
	v_lshl_add_u64 v[226:227], s[54:55], 0, v[130:131]
	s_mov_b32 m0, s62
	s_nop 0
	global_load_lds_dwordx4 v[226:227], off
	s_waitcnt vmcnt(8)
	s_waitcnt lgkmcnt(0)
	s_barrier
	s_setprio 1
	s_waitcnt lgkmcnt(0)
	v_mfma_f32_16x16x32_bf16 v[124:127], v[150:153], v[186:189], v[124:127]
	v_mfma_f32_16x16x32_bf16 v[120:123], v[158:161], v[186:189], v[120:123]
	v_mfma_f32_16x16x32_bf16 v[108:111], v[150:153], v[194:197], v[108:111]
	v_mfma_f32_16x16x32_bf16 v[104:107], v[158:161], v[194:197], v[104:107]
	v_mfma_f32_16x16x32_bf16 v[92:95], v[150:153], v[202:205], v[92:95]
	v_mfma_f32_16x16x32_bf16 v[88:91], v[158:161], v[202:205], v[88:91]
	v_mfma_f32_16x16x32_bf16 v[76:79], v[150:153], v[214:217], v[76:79]
	v_mfma_f32_16x16x32_bf16 v[72:75], v[158:161], v[214:217], v[72:75]
	v_mfma_f32_16x16x32_bf16 v[124:127], v[154:157], v[190:193], v[124:127]
	v_mfma_f32_16x16x32_bf16 v[120:123], v[162:165], v[190:193], v[120:123]
	v_mfma_f32_16x16x32_bf16 v[108:111], v[154:157], v[198:201], v[108:111]
	v_mfma_f32_16x16x32_bf16 v[104:107], v[162:165], v[198:201], v[104:107]
	v_mfma_f32_16x16x32_bf16 v[92:95], v[154:157], v[210:213], v[92:95]
	v_mfma_f32_16x16x32_bf16 v[88:91], v[162:165], v[210:213], v[88:91]
	v_mfma_f32_16x16x32_bf16 v[76:79], v[154:157], v[218:221], v[76:79]
	v_mfma_f32_16x16x32_bf16 v[72:75], v[162:165], v[218:221], v[72:75]
	s_setprio 0
	s_setprio 1
	v_mfma_f32_16x16x32_bf16 v[116:119], v[170:173], v[186:189], v[116:119]
	v_mfma_f32_16x16x32_bf16 v[112:115], v[178:181], v[186:189], v[112:115]
	v_mfma_f32_16x16x32_bf16 v[100:103], v[170:173], v[194:197], v[100:103]
	v_mfma_f32_16x16x32_bf16 v[96:99], v[178:181], v[194:197], v[96:99]
	v_mfma_f32_16x16x32_bf16 v[84:87], v[170:173], v[202:205], v[84:87]
	v_mfma_f32_16x16x32_bf16 v[80:83], v[178:181], v[202:205], v[80:83]
	v_mfma_f32_16x16x32_bf16 v[68:71], v[170:173], v[214:217], v[68:71]
	v_mfma_f32_16x16x32_bf16 v[64:67], v[178:181], v[214:217], v[64:67]
	v_mfma_f32_16x16x32_bf16 v[116:119], v[174:177], v[190:193], v[116:119]
	v_mfma_f32_16x16x32_bf16 v[112:115], v[182:185], v[190:193], v[112:115]
	v_mfma_f32_16x16x32_bf16 v[100:103], v[174:177], v[198:201], v[100:103]
	v_mfma_f32_16x16x32_bf16 v[96:99], v[182:185], v[198:201], v[96:99]
	v_mfma_f32_16x16x32_bf16 v[84:87], v[174:177], v[210:213], v[84:87]
	v_mfma_f32_16x16x32_bf16 v[80:83], v[182:185], v[210:213], v[80:83]
	v_mfma_f32_16x16x32_bf16 v[68:71], v[174:177], v[218:221], v[68:71]
	v_mfma_f32_16x16x32_bf16 v[64:67], v[182:185], v[218:221], v[64:67]
	s_setprio 0
	s_barrier
; #define PG8_STAGE(bufoff, gbase, voff) do { _Pragma("unroll") for (int _i = 0; _i < 2; ++_i) \
;         __builtin_amdgcn_global_load_lds((const unsigned*)((const char*)(gbase) + (voff)[_i]), (PG8_LAS unsigned*)(lds + (bufoff) + ldsw + _i * 8192), 16, 0, 0); } while (0)
; #define PG8_LDA(dst, b, h) do { _Pragma("unroll") for (int m = 0; m < 4; ++m) _Pragma("unroll") for (int k = 0; k < 2; ++k) dst[m][k] = *(const PG8_LAS bf16x8*)(lds + PG8_SA(b, h) + aoff + m * 2048 + k * 1024); } while (0)
; #define PG8_MMA(ai, bj, At, Bt) do { __builtin_amdgcn_s_setprio(1); _Pragma("unroll") for (int m = 0; m < 4; ++m) _Pragma("unroll") for (int n = 0; n < 2; ++n) _Pragma("unroll") for (int k = 0; k < 2; ++k) \
;         acc[ai][bj][m][n] = __builtin_amdgcn_mfma_f32_16x16x32_bf16(Bt[n][k], At[m][k], acc[ai][bj][m][n], 0, 0, 0); __builtin_amdgcn_s_setprio(0); } while (0)
; #define PG8_WAIT_V(n) asm volatile("s_waitcnt vmcnt(" #n ")" ::: "memory")
; #define PG8_WAIT_L(n) asm volatile("s_waitcnt lgkmcnt(" #n ")" ::: "memory")
; #define PG8_BAR __builtin_amdgcn_s_barrier()
; #define PG8_SCHED __builtin_amdgcn_sched_barrier(0)
; template <class Epi, class Sched, bool ALIGN_EPI = false, bool SP2 = false>
; __device__ __forceinline__ void gemm_phase(PG8_LAS unsigned char* lds, const Gemm g, const Sched& S, const Epi& E) {
;     ...
;         for (int t = 0; t < nt; t += 2) {
;     ...
;             PG8_LDA(At, 1, 1); PG8_STAGE(PG8_SB(1, 0), b3, voffB); PG8_STAGE(PG8_SB(1, 1), b3 + hstepB, voffB); PG8_STAGE(PG8_SA(1, 0), a3, voffA);
;             PG8_WAIT_V(8); PG8_WAIT_L(0); PG8_BAR; PG8_MMA(1, 0, At, B0); PG8_MMA(1, 1, At, B1); PG8_BAR; PG8_SCHED;
	s_add_i32 s54, s76, s3
	v_lshl_add_u64 v[166:167], v[166:167], 0, s[26:27]
	s_mov_b32 m0, s54
	ds_read_b128 v[186:189], v149 offset:49152
	ds_read_b128 v[190:193], v149 offset:50176
	ds_read_b128 v[194:197], v149 offset:51200
	ds_read_b128 v[198:201], v149 offset:52224
	ds_read_b128 v[202:205], v149 offset:53248
	ds_read_b128 v[210:213], v149 offset:54272
	ds_read_b128 v[214:217], v149 offset:55296
	ds_read_b128 v[218:221], v149 offset:56320
	global_load_lds_dwordx4 v[166:167], off
	s_add_i32 m0, s54, 0x2000
	s_add_u32 s52, s52, 0x80080
	v_lshl_add_u64 v[166:167], v[206:207], 0, s[26:27]
	s_addc_u32 s53, s53, 0
	s_add_i32 s54, s77, s3
	global_load_lds_dwordx4 v[166:167], off
	v_lshl_add_u64 v[166:167], s[52:53], 0, v[132:133]
	s_mov_b32 m0, s54
	s_nop 0
	global_load_lds_dwordx4 v[166:167], off
	v_lshl_add_u64 v[166:167], s[52:53], 0, v[128:129]
	s_add_i32 m0, s54, 0x2000
	s_nop 0
	global_load_lds_dwordx4 v[166:167], off
	v_lshl_add_u64 v[166:167], v[222:223], 0, s[26:27]
	s_mov_b32 m0, s64
	s_nop 0
	global_load_lds_dwordx4 v[166:167], off
	v_lshl_add_u64 v[166:167], v[224:225], 0, s[26:27]
	s_mov_b32 m0, s65
	s_nop 0
	global_load_lds_dwordx4 v[166:167], off
	s_waitcnt vmcnt(8)
	s_waitcnt lgkmcnt(0)
	s_barrier
	s_setprio 1
	s_waitcnt lgkmcnt(0)
	v_mfma_f32_16x16x32_bf16 v[60:63], v[150:153], v[186:189], v[60:63]
	v_mfma_f32_16x16x32_bf16 v[56:59], v[158:161], v[186:189], v[56:59]
	v_mfma_f32_16x16x32_bf16 v[44:47], v[150:153], v[194:197], v[44:47]
	v_mfma_f32_16x16x32_bf16 v[40:43], v[158:161], v[194:197], v[40:43]
	v_mfma_f32_16x16x32_bf16 v[28:31], v[150:153], v[202:205], v[28:31]
	v_mfma_f32_16x16x32_bf16 v[24:27], v[158:161], v[202:205], v[24:27]
	v_mfma_f32_16x16x32_bf16 v[12:15], v[150:153], v[214:217], v[12:15]
	v_mfma_f32_16x16x32_bf16 v[8:11], v[158:161], v[214:217], v[8:11]
	v_mfma_f32_16x16x32_bf16 v[60:63], v[154:157], v[190:193], v[60:63]
	v_mfma_f32_16x16x32_bf16 v[56:59], v[162:165], v[190:193], v[56:59]
	v_mfma_f32_16x16x32_bf16 v[44:47], v[154:157], v[198:201], v[44:47]
	v_mfma_f32_16x16x32_bf16 v[40:43], v[162:165], v[198:201], v[40:43]
	v_mfma_f32_16x16x32_bf16 v[28:31], v[154:157], v[210:213], v[28:31]
	v_mfma_f32_16x16x32_bf16 v[24:27], v[162:165], v[210:213], v[24:27]
	v_mfma_f32_16x16x32_bf16 v[12:15], v[154:157], v[218:221], v[12:15]
	v_mfma_f32_16x16x32_bf16 v[8:11], v[162:165], v[218:221], v[8:11]
	s_setprio 0
	s_setprio 1
	v_mfma_f32_16x16x32_bf16 v[52:55], v[170:173], v[186:189], v[52:55]
	v_mfma_f32_16x16x32_bf16 v[48:51], v[178:181], v[186:189], v[48:51]
	v_mfma_f32_16x16x32_bf16 v[36:39], v[170:173], v[194:197], v[36:39]
	v_mfma_f32_16x16x32_bf16 v[32:35], v[178:181], v[194:197], v[32:35]
	v_mfma_f32_16x16x32_bf16 v[20:23], v[170:173], v[202:205], v[20:23]
	v_mfma_f32_16x16x32_bf16 v[16:19], v[178:181], v[202:205], v[16:19]
	v_mfma_f32_16x16x32_bf16 v[4:7], v[170:173], v[214:217], v[4:7]
	v_mfma_f32_16x16x32_bf16 v[0:3], v[178:181], v[214:217], v[0:3]
	v_mfma_f32_16x16x32_bf16 v[52:55], v[174:177], v[190:193], v[52:55]
	v_mfma_f32_16x16x32_bf16 v[48:51], v[182:185], v[190:193], v[48:51]
	v_mfma_f32_16x16x32_bf16 v[36:39], v[174:177], v[198:201], v[36:39]
	v_mfma_f32_16x16x32_bf16 v[32:35], v[182:185], v[198:201], v[32:35]
	v_mfma_f32_16x16x32_bf16 v[20:23], v[174:177], v[210:213], v[20:23]
	v_mfma_f32_16x16x32_bf16 v[16:19], v[182:185], v[210:213], v[16:19]
	v_mfma_f32_16x16x32_bf16 v[4:7], v[174:177], v[218:221], v[4:7]
	v_mfma_f32_16x16x32_bf16 v[0:3], v[182:185], v[218:221], v[0:3]
	s_setprio 0
	s_add_i32 s75, s75, 2
	s_add_u32 s50, s50, 0x100
	s_addc_u32 s51, s51, 0
	s_add_u32 s73, s73, 0x100
	s_addc_u32 s74, s74, 0
	s_cmp_gt_u32 s75, 29
	s_barrier
	s_cbranch_scc0 .LBB0_866
	s_and_b64 vcc, exec, s[30:31]
	s_cbranch_vccz .LBB0_869
	s_barrier
